# compress unit: one line-touch load per wave prefetches the unit's 512 KV lines (shared A operand) before the 16-step K loop
# speedup vs baseline: 1.0089x; 1.0051x over previous
.LBB0_879:
	s_and_b64 vcc, exec, s[38:39]
	s_cbranch_vccz .LBB0_824
	s_bfe_u32 s44, s33, 0x10003
	s_lshl_b32 s38, s44, 7
	v_add_u32_e32 v2, s38, v146
	v_readlane_b32 s38, v254, 6
	v_readlane_b32 s39, v254, 7
	s_load_dwordx2 s[40:41], s[38:39], 0x50
	s_lshl_b32 s42, s44, 15
	v_ashrrev_i32_e32 v3, 31, v2
	s_load_dwordx2 s[38:39], s[38:39], 0xa0
	v_lshlrev_b64 v[50:51], 12, v[2:3]
	s_waitcnt lgkmcnt(0)
	s_add_u32 s40, s40, s42
	s_addc_u32 s41, s41, 0
	v_lshl_add_u64 v[2:3], v[88:89], 2, s[40:41]
	v_lshl_add_u64 v[4:5], v[90:91], 2, s[40:41]
	global_load_dwordx4 v[34:37], v[2:3], off
	global_load_dwordx4 v[38:41], v[4:5], off
	v_lshl_add_u64 v[2:3], v[92:93], 2, s[40:41]
	v_lshl_add_u64 v[4:5], v[94:95], 2, s[40:41]
	s_lshl_b32 s40, s33, 4
	s_ashr_i32 s42, s33, 5
	s_and_b32 s45, s40, 0x70
	v_or_b32_e32 v0, s45, v145
	s_lshl_b32 s40, s42, 11
	global_load_dwordx4 v[42:45], v[2:3], off
	global_load_dwordx4 v[46:49], v[4:5], off
	v_lshl_or_b32 v0, v0, 4, s40
	v_mov_b64_e32 v[2:3], s[38:39]
	s_movk_i32 s40, 0x600
	v_readlane_b32 s48, v254, 13
	s_bfe_u32 s43, s33, 0x10004
	v_mad_i64_i32 v[2:3], s[40:41], v0, s40, v[2:3]
	v_readlane_b32 s49, v254, 14
	s_lshl_b32 s40, s44, 8
	s_lshl_b32 s43, s43, 7
	s_mov_b32 s41, s49
	s_or_b32 s48, s43, s40
	v_writelane_b32 v254, s40, 13
	v_lshl_add_u64 v[2:3], v[2:3], 0, s[48:49]
	v_mov_b32_e32 v111, v1
	v_writelane_b32 v254, s41, 14
	s_mov_b64 s[40:41], 0x9600000
	v_lshl_add_u64 v[70:71], v[2:3], 0, s[40:41]
	v_readlane_b32 s32, v254, 3
	v_lshrrev_b32_e32 v246, 4, v202
	s_lshl_b32 s32, s32, 2
	v_add_u32_e32 v246, s32, v246
	v_mul_u32_u24_e32 v246, 0x600, v246
	v_mov_b32_e32 v247, 0
	v_lshl_add_u64 v[246:247], v[70:71], 0, v[246:247]
	global_load_dword v242, v[246:247], off
	v_lshl_add_u64 v[2:3], s[38:39], 0, v[50:51]
	v_lshl_add_u64 v[2:3], v[96:97], 1, v[2:3]
	s_mov_b64 s[40:41], 0x600000
	v_lshl_add_u64 v[4:5], v[98:99], 1, v[70:71]
	v_lshl_add_u64 v[22:23], v[2:3], 0, s[40:41]
	s_mov_b32 s40, 0x600000
	v_lshl_add_u64 v[18:19], v[102:103], 1, v[70:71]
	v_lshl_add_u64 v[10:11], v[4:5], 0, v[110:111]
	v_add_co_u32_e32 v2, vcc, s40, v2
	v_lshl_add_u64 v[4:5], v[100:101], 1, v[70:71]
	v_mov_b32_e32 v113, v1
	v_lshl_add_u64 v[24:25], v[18:19], 0, v[110:111]
	v_lshl_add_u64 v[18:19], v[104:105], 1, v[70:71]
	v_mov_b32_e32 v115, v1
	v_addc_co_u32_e32 v3, vcc, 0, v3, vcc
	v_lshl_add_u64 v[4:5], v[4:5], 0, v[112:113]
	v_lshl_add_u64 v[30:31], v[18:19], 0, v[114:115]
	global_load_dwordx4 v[6:9], v[2:3], off
	s_nop 0
	global_load_dwordx4 v[2:5], v[4:5], off
	s_nop 0
	global_load_dwordx4 v[10:13], v[10:11], off
	s_nop 0
	global_load_dwordx4 v[14:17], v[22:23], off offset:64
	global_load_dwordx4 v[18:21], v[22:23], off offset:128
	global_load_dwordx4 v[26:29], v[22:23], off offset:192
	s_nop 0
	global_load_dwordx4 v[22:25], v[24:25], off
	s_nop 0
	global_load_dwordx4 v[30:33], v[30:31], off
	s_mov_b32 s46, 0
	v_lshl_add_u64 v[72:73], v[70:71], 0, v[110:111]
	v_mov_b32_e32 v76, v158
	s_waitcnt vmcnt(11)
	ds_write_b128 v161, v[34:37] offset:12416
	s_waitcnt vmcnt(10)
	ds_write_b128 v161, v[38:41] offset:20608
	s_waitcnt vmcnt(9)
	ds_write_b128 v161, v[42:45] offset:28800
	s_waitcnt vmcnt(8)
	ds_write_b128 v161, v[46:49] offset:36992
	v_lshl_add_u64 v[34:35], s[38:39], 0, v[108:109]
	v_lshl_add_u64 v[74:75], v[34:35], 0, v[50:51]
	v_mov_b32_e32 v50, 0
	v_mov_b32_e32 v51, v50
	v_mov_b32_e32 v52, v50
	v_mov_b32_e32 v53, v50
	s_branch .LBB0_882

.LBB0_2066:
	s_and_b64 vcc, exec, s[38:39]
	s_cbranch_vccz .LBB0_2011
	s_load_dwordx2 s[40:41], s[68:69], 0x50
	s_load_dwordx2 s[38:39], s[68:69], 0xa0
	s_bfe_u32 s44, s33, 0x10003
	s_or_b32 s46, s44, 2
	s_lshl_b32 s42, s46, 15
	s_waitcnt lgkmcnt(0)
	s_add_u32 s40, s40, s42
	s_addc_u32 s41, s41, 0
	v_lshl_add_u64 v[2:3], v[88:89], 2, s[40:41]
	v_lshl_add_u64 v[4:5], v[90:91], 2, s[40:41]
	global_load_dwordx4 v[34:37], v[2:3], off
	global_load_dwordx4 v[38:41], v[4:5], off
	v_lshl_add_u64 v[2:3], v[92:93], 2, s[40:41]
	v_lshl_add_u64 v[4:5], v[94:95], 2, s[40:41]
	s_lshl_b32 s40, s33, 4
	s_ashr_i32 s42, s33, 5
	s_and_b32 s45, s40, 0x70
	v_or_b32_e32 v0, s45, v145
	s_lshl_b32 s40, s42, 11
	global_load_dwordx4 v[42:45], v[2:3], off
	global_load_dwordx4 v[46:49], v[4:5], off
	v_lshl_or_b32 v0, v0, 4, s40
	v_mov_b64_e32 v[2:3], s[38:39]
	s_movk_i32 s40, 0x600
	v_readlane_b32 s48, v255, 32
	s_bfe_u32 s43, s33, 0x10004
	v_mad_i64_i32 v[2:3], s[40:41], v0, s40, v[2:3]
	v_readlane_b32 s49, v255, 33
	s_lshl_b32 s43, s43, 7
	s_lshl_b32 s40, s44, 8
	s_mov_b32 s41, s49
	s_or_b32 s48, s40, s43
	v_writelane_b32 v255, s40, 32
	v_lshl_add_u64 v[2:3], v[2:3], 0, s[48:49]
	v_mov_b32_e32 v111, v1
	v_writelane_b32 v255, s41, 33
	s_mov_b64 s[40:41], 0x9600000
	v_lshl_add_u64 v[70:71], v[2:3], 0, s[40:41]
	v_readlane_b32 s32, v254, 3
	v_lshrrev_b32_e32 v246, 4, v202
	s_lshl_b32 s32, s32, 2
	v_add_u32_e32 v246, s32, v246
	v_mul_u32_u24_e32 v246, 0x600, v246
	v_mov_b32_e32 v247, 0
	v_lshl_add_u64 v[246:247], v[70:71], 0, v[246:247]
	global_load_dword v242, v[246:247], off
	v_lshl_add_u32 v2, s46, 7, v146
	v_ashrrev_i32_e32 v3, 31, v2
	v_lshlrev_b64 v[2:3], 12, v[2:3]
	v_lshl_add_u64 v[2:3], s[38:39], 0, v[2:3]
	v_lshl_add_u64 v[2:3], v[96:97], 1, v[2:3]
	s_mov_b64 s[40:41], 0x600000
	v_lshl_add_u64 v[4:5], v[98:99], 1, v[70:71]
	v_lshl_add_u64 v[22:23], v[2:3], 0, s[40:41]
	s_mov_b32 s40, 0x600000
	v_lshl_add_u64 v[18:19], v[102:103], 1, v[70:71]
	v_lshl_add_u64 v[10:11], v[4:5], 0, v[110:111]
	v_add_co_u32_e32 v2, vcc, s40, v2
	v_lshl_add_u64 v[4:5], v[100:101], 1, v[70:71]
	v_mov_b32_e32 v113, v1
	v_lshl_add_u64 v[24:25], v[18:19], 0, v[110:111]
	v_lshl_add_u64 v[18:19], v[104:105], 1, v[70:71]
	v_mov_b32_e32 v115, v1
	v_addc_co_u32_e32 v3, vcc, 0, v3, vcc
	v_lshl_add_u64 v[4:5], v[4:5], 0, v[112:113]
	v_lshl_add_u64 v[30:31], v[18:19], 0, v[114:115]
	global_load_dwordx4 v[6:9], v[2:3], off
	s_nop 0
	global_load_dwordx4 v[2:5], v[4:5], off
	s_nop 0
	global_load_dwordx4 v[10:13], v[10:11], off
	s_nop 0
	global_load_dwordx4 v[14:17], v[22:23], off offset:64
	global_load_dwordx4 v[18:21], v[22:23], off offset:128
	global_load_dwordx4 v[26:29], v[22:23], off offset:192
	s_nop 0
	global_load_dwordx4 v[22:25], v[24:25], off
	s_nop 0
	global_load_dwordx4 v[30:33], v[30:31], off
	v_lshl_add_u32 v50, s44, 7, v158
	v_ashrrev_i32_e32 v51, 31, v50
	v_lshlrev_b64 v[50:51], 12, v[50:51]
	s_mov_b32 s47, 0
	v_lshl_add_u64 v[72:73], v[70:71], 0, v[110:111]
	v_mov_b32_e32 v76, v159
	s_waitcnt vmcnt(11)
	ds_write_b128 v162, v[34:37] offset:12416
	s_waitcnt vmcnt(10)
	ds_write_b128 v162, v[38:41] offset:20608
	s_waitcnt vmcnt(9)
	ds_write_b128 v162, v[42:45] offset:28800
	s_waitcnt vmcnt(8)
	ds_write_b128 v162, v[46:49] offset:36992
	v_lshl_add_u64 v[34:35], s[38:39], 0, v[108:109]
	v_lshl_add_u64 v[74:75], v[34:35], 0, v[50:51]
	v_mov_b32_e32 v50, 0
	v_mov_b32_e32 v51, v50
	v_mov_b32_e32 v52, v50
	v_mov_b32_e32 v53, v50
	s_branch .LBB0_2069
